# skip the grid barrier after the last layer's gather (the kernel ends there, nothing is ordered by it)
# speedup vs baseline: 1.0062x; 1.0062x over previous
; __device__ __forceinline__ unsigned xb_ld(unsigned* p)              { return __hip_atomic_load(p, __ATOMIC_RELAXED, __HIP_MEMORY_SCOPE_AGENT); }
; __device__ __forceinline__ unsigned xb_add(unsigned* p, unsigned v) { return __hip_atomic_fetch_add(p, v, __ATOMIC_RELAXED, __HIP_MEMORY_SCOPE_AGENT); }
; #define XB_SPIN(cond, bar) do { unsigned _sp = 0; while (cond) { __builtin_amdgcn_s_sleep(1); \
;     if ((++_sp & 255u) == 0u) { if (xb_ld(&(bar)[XB_TMO])) break; if (_sp > XB_SPIN_CAP) { atomicAdd(&(bar)[XB_TMO], 1u); break; } } } } while (0)
; #define BAR() do { XcdBarrier bb_; bb_.bar = a.bar; asm volatile("" : "+s"(bb_.bar)); unsigned bx_ = bar_x; asm volatile("" : "+s"(bx_)); bb_.x = bx_; bb_.st = (volatile LAS unsigned*)(lds + LDS_BYTES - 64); xcd_barrier(bb_); } while (0)
; __device__ __forceinline__ void xcd_barrier(const XcdBarrier& b) {
;     asm volatile("s_waitcnt vmcnt(0)" ::: "memory");
;     __syncthreads();
;     if (threadIdx.x == 0) {
;         unsigned* bar = b.bar;
;         __builtin_amdgcn_s_waitcnt(0);
;         unsigned nloc = b.st[0], nx = b.st[1];
;         if (nloc == 0u) { xcd_barrier_complete(bar, b.x, nloc, nx); b.st[0] = nloc; b.st[1] = nx; }
;         const unsigned old = xb_add(&bar[XB_XSUB(b.x)], 1u);
;         const unsigned gen = old / nloc;
;         if (old + 1u == (gen + 1u) * nloc) {
;             __builtin_amdgcn_fence(__ATOMIC_RELEASE, "agent");
;             asm volatile("s_waitcnt vmcnt(0)" ::: "memory");
;             const unsigned og = xb_add(&bar[XB_TOP], 1u);
;             const unsigned tg = og / nx;
;             if (og + 1u == (tg + 1u) * nx) xb_add(&bar[XB_TOPGEN], 1u);
;             else XB_SPIN(xb_ld(&bar[XB_TOPGEN]) == tg, bar);
;             __builtin_amdgcn_fence(__ATOMIC_ACQUIRE, "agent");
;             xb_add(&bar[XB_XGEN(b.x)], 1u);
;             asm volatile("s_waitcnt vmcnt(0)" ::: "memory");
;         } else {
;             XB_SPIN(xb_ld(&bar[XB_XGEN(b.x)]) == gen, bar);
;             __builtin_amdgcn_fence(__ATOMIC_ACQUIRE, "agent");
;             asm volatile("s_waitcnt vmcnt(0)" ::: "memory");
;         }
;     }
;     __syncthreads();
; __global__ void __launch_bounds__(NTHR, 2) mega_fwd(Args a) {
;     ...
;         BAR();
;     }
.LBB0_1163:
	v_readlane_b32 s98, v253, 41
	s_nop 0
	s_cmp_eq_u32 s98, 3
	s_cbranch_scc1 .Lskip_last_bar
	s_mov_b64 s[42:43], s[76:77]
	s_mov_b32 s36, s69
	s_waitcnt vmcnt(0)
	s_waitcnt lgkmcnt(0)
	s_barrier
	s_and_saveexec_b64 s[40:41], s[78:79]
	v_readlane_b32 s58, v253, 36
	v_readlane_b32 s46, v253, 21
	v_readlane_b32 s59, v253, 37
	v_readlane_b32 s57, v253, 38
	v_readlane_b32 s47, v253, 22
	s_cbranch_execnz .LBB0_1164
	s_getpc_b64 s[98:99]

; __global__ void __launch_bounds__(NTHR, 2) mega_fwd(Args a) {
;     ...
;     }
;     ...
; }
.Lskip_last_bar:
.LBB0_1206:
	s_endpgm
